# attention tile loops: far-tile bias via v_fma (no broadcast movs), shared ds_read2 base, mov+pk_mul to two muls, 64-byte aligned loop heads
# speedup vs baseline: 1.0423x; 1.0016x over previous
.LBB0_285:
	s_or_b64 exec, exec, s[2:3]
	s_mov_b32 s37, 0
	s_cmp_lt_i32 s29, 0
	v_cmp_gt_u32_e64 s[6:7], 32, v213
	s_cbranch_scc1 .LBB0_315
	v_and_b32_e32 v0, 16, v182
	v_and_b32_e32 v104, 3, v182
	v_or3_b32 v0, v99, v0, v104
	v_lshlrev_b32_e32 v104, 8, v0
	v_lshlrev_b32_e32 v0, 2, v0
	v_and_b32_e32 v0, 12, v0
	v_lshrrev_b32_e32 v99, 2, v99
	v_bitop3_b32 v105, v0, v98, v99 bitop3:0x36
	v_lshl_or_b32 v214, v105, 4, v104
	v_or_b32_e32 v105, 2, v98
	v_bitop3_b32 v105, v0, v105, v99 bitop3:0x36
	v_lshl_or_b32 v215, v105, 4, v104
	v_or_b32_e32 v105, 4, v98
	v_bitop3_b32 v105, v0, v105, v99 bitop3:0x36
	v_lshl_or_b32 v216, v105, 4, v104
	v_or_b32_e32 v105, 6, v98
	v_bitop3_b32 v105, v0, v105, v99 bitop3:0x36
	v_lshl_or_b32 v217, v105, 4, v104
	v_or_b32_e32 v105, 8, v98
	v_bitop3_b32 v105, v0, v105, v99 bitop3:0x36
	v_lshl_or_b32 v218, v105, 4, v104
	v_or_b32_e32 v105, 10, v98
	v_bitop3_b32 v105, v0, v105, v99 bitop3:0x36
	v_lshl_or_b32 v219, v105, 4, v104
	v_or_b32_e32 v105, 12, v98
	v_bitop3_b32 v105, v0, v105, v99 bitop3:0x36
	v_lshl_or_b32 v220, v105, 4, v104
	v_or_b32_e32 v105, 14, v98
	v_bitop3_b32 v0, v0, v105, v99 bitop3:0x36
	v_lshl_or_b32 v221, v0, 4, v104
	v_lshrrev_b32_e32 v0, 2, v212
	v_lshlrev_b32_e32 v104, 1, v210
	v_lshlrev_b32_e32 v106, 1, v98
	v_or_b32_e32 v99, v183, v0
	v_and_b32_e32 v104, 2, v104
	v_bfe_u32 v105, v182, 1, 1
	v_lshlrev_b32_e32 v134, 6, v0
	v_or_b32_e32 v0, 1, v106
	v_bitop3_b32 v0, v104, v0, v105 bitop3:0x36
	v_lshlrev_b32_e32 v135, 4, v0
	s_waitcnt vmcnt(0)
	v_add_f32_e32 v0, v62, v63
	v_add_f32_e32 v62, v64, v65
	v_add_f32_e32 v0, v0, v62
	v_fmamk_f32 v0, v0, 0x3c000000, v252
	s_mov_b32 s0, 0xf800000
	v_mul_f32_e32 v62, 0x4f800000, v0
	v_cmp_gt_f32_e32 vcc, s0, v0
	v_bitop3_b32 v133, v104, v106, v105 bitop3:0x36
	v_lshlrev_b32_e32 v107, 3, v182
	v_cndmask_b32_e32 v0, v0, v62, vcc
	v_sqrt_f32_e32 v62, v0
	v_and_b32_e32 v132, 8, v107
	v_xor_b32_e32 v64, 64, v134
	v_xor_b32_e32 v65, 0x80, v134
	v_add_u32_e32 v63, -1, v62
	v_fma_f32 v104, -v63, v62, v0
	v_cmp_ge_f32_e64 s[8:9], 0, v104
	v_add_u32_e32 v104, 1, v62
	v_xor_b32_e32 v136, 0xc0, v134
	v_cndmask_b32_e64 v63, v62, v63, s[8:9]
	v_fma_f32 v62, -v104, v62, v0
	v_cmp_lt_f32_e64 s[8:9], 0, v62
	s_ashr_i32 s13, s19, 7
	s_add_i32 s13, s13, s18
	v_cndmask_b32_e64 v62, v63, v104, s[8:9]
	v_mul_f32_e32 v63, 0x37800000, v62
	v_cndmask_b32_e32 v62, v62, v63, vcc
	v_cmp_class_f32_e32 vcc, v0, v253
	s_sub_i32 s31, s18, s23
	s_add_i32 s29, s29, -2
	v_cndmask_b32_e32 v0, v62, v0, vcc
	v_div_scale_f32 v62, s[0:1], v0, v0, 1.0
	v_rcp_f32_e32 v63, v62
	s_add_i32 s0, 0, 0x18000
	v_lshl_add_u32 v228, v98, 5, s0
	s_lshl_b32 s0, s23, 8
	v_fma_f32 v104, -v62, v63, 1.0
	v_fmac_f32_e32 v63, v104, v63
	v_div_scale_f32 v104, vcc, 1.0, v0, 1.0
	v_mul_f32_e32 v105, v104, v63
	v_fma_f32 v106, -v62, v105, v104
	v_fmac_f32_e32 v105, v106, v63
	v_fma_f32 v62, -v62, v105, v104
	v_div_fmas_f32 v62, v62, v63, v105
	v_div_fixup_f32 v0, v62, v0, 1.0
	v_lshlrev_b32_e32 v62, 16, v30
	v_and_b32_e32 v63, 0xffff0000, v30
	v_lshlrev_b32_e32 v30, 16, v31
	v_and_b32_e32 v31, 0xffff0000, v31
	v_pk_mul_f32 v[30:31], v[0:1], v[30:31] op_sel_hi:[0,1]
	v_pk_mul_f32 v[62:63], v[0:1], v[62:63] op_sel_hi:[0,1]
	s_waitcnt lgkmcnt(0)
	v_pk_mul_f32 v[30:31], v[30:31], v[102:103]
	v_pk_mul_f32 v[62:63], v[62:63], v[100:101]
	v_cvt_pk_bf16_f32 v101, v30, v31
	v_lshlrev_b32_e32 v30, 16, v32
	v_and_b32_e32 v31, 0xffff0000, v32
	v_pk_mul_f32 v[30:31], v[0:1], v[30:31] op_sel_hi:[0,1]
	v_pk_mul_f32 v[30:31], v[30:31], v[94:95]
	v_cvt_pk_bf16_f32 v100, v62, v63
	v_cvt_pk_bf16_f32 v102, v30, v31
	v_lshlrev_b32_e32 v30, 16, v33
	v_and_b32_e32 v31, 0xffff0000, v33
	v_pk_mul_f32 v[30:31], v[0:1], v[30:31] op_sel_hi:[0,1]
	v_pk_mul_f32 v[30:31], v[30:31], v[96:97]
	s_add_i32 s30, s13, -8
	v_cvt_pk_bf16_f32 v103, v30, v31
	v_lshlrev_b32_e32 v30, 16, v26
	v_and_b32_e32 v31, 0xffff0000, v26
	v_lshlrev_b32_e32 v26, 16, v27
	v_and_b32_e32 v27, 0xffff0000, v27
	v_pk_mul_f32 v[26:27], v[0:1], v[26:27] op_sel_hi:[0,1]
	v_pk_mul_f32 v[26:27], v[26:27], v[92:93]
	v_pk_mul_f32 v[30:31], v[0:1], v[30:31] op_sel_hi:[0,1]
	v_cvt_pk_bf16_f32 v105, v26, v27
	v_lshlrev_b32_e32 v26, 16, v28
	v_and_b32_e32 v27, 0xffff0000, v28
	v_pk_mul_f32 v[26:27], v[0:1], v[26:27] op_sel_hi:[0,1]
	v_pk_mul_f32 v[26:27], v[26:27], v[86:87]
	v_pk_mul_f32 v[30:31], v[30:31], v[90:91]
	v_cvt_pk_bf16_f32 v106, v26, v27
	v_lshlrev_b32_e32 v26, 16, v29
	v_and_b32_e32 v27, 0xffff0000, v29
	v_pk_mul_f32 v[26:27], v[0:1], v[26:27] op_sel_hi:[0,1]
	v_pk_mul_f32 v[26:27], v[26:27], v[88:89]
	v_cvt_pk_bf16_f32 v104, v30, v31
	v_cvt_pk_bf16_f32 v107, v26, v27
	v_lshlrev_b32_e32 v26, 16, v22
	v_and_b32_e32 v27, 0xffff0000, v22
	v_lshlrev_b32_e32 v22, 16, v23
	v_and_b32_e32 v23, 0xffff0000, v23
	v_pk_mul_f32 v[22:23], v[0:1], v[22:23] op_sel_hi:[0,1]
	v_pk_mul_f32 v[22:23], v[22:23], v[84:85]
	v_pk_mul_f32 v[26:27], v[0:1], v[26:27] op_sel_hi:[0,1]
	v_cvt_pk_bf16_f32 v109, v22, v23
	v_lshlrev_b32_e32 v22, 16, v24
	v_and_b32_e32 v23, 0xffff0000, v24
	v_pk_mul_f32 v[22:23], v[0:1], v[22:23] op_sel_hi:[0,1]
	v_pk_mul_f32 v[22:23], v[22:23], v[78:79]
	v_pk_mul_f32 v[26:27], v[26:27], v[82:83]
	v_cvt_pk_bf16_f32 v110, v22, v23
	v_lshlrev_b32_e32 v22, 16, v25
	v_and_b32_e32 v23, 0xffff0000, v25
	v_pk_mul_f32 v[22:23], v[0:1], v[22:23] op_sel_hi:[0,1]
	v_pk_mul_f32 v[22:23], v[22:23], v[80:81]
	v_cvt_pk_bf16_f32 v108, v26, v27
	v_cvt_pk_bf16_f32 v111, v22, v23
	v_lshlrev_b32_e32 v22, 16, v18
	v_and_b32_e32 v23, 0xffff0000, v18
	v_lshlrev_b32_e32 v18, 16, v19
	v_and_b32_e32 v19, 0xffff0000, v19
	v_pk_mul_f32 v[18:19], v[0:1], v[18:19] op_sel_hi:[0,1]
	v_pk_mul_f32 v[18:19], v[18:19], v[76:77]
	v_pk_mul_f32 v[22:23], v[0:1], v[22:23] op_sel_hi:[0,1]
	v_cvt_pk_bf16_f32 v113, v18, v19
	v_lshlrev_b32_e32 v18, 16, v20
	v_and_b32_e32 v19, 0xffff0000, v20
	v_pk_mul_f32 v[18:19], v[0:1], v[18:19] op_sel_hi:[0,1]
	v_pk_mul_f32 v[18:19], v[18:19], v[70:71]
	v_pk_mul_f32 v[22:23], v[22:23], v[74:75]
	v_cvt_pk_bf16_f32 v114, v18, v19
	v_lshlrev_b32_e32 v18, 16, v21
	v_and_b32_e32 v19, 0xffff0000, v21
	v_pk_mul_f32 v[18:19], v[0:1], v[18:19] op_sel_hi:[0,1]
	v_pk_mul_f32 v[18:19], v[18:19], v[72:73]
	v_cvt_pk_bf16_f32 v112, v22, v23
	v_cvt_pk_bf16_f32 v115, v18, v19
	v_lshlrev_b32_e32 v18, 16, v14
	v_and_b32_e32 v19, 0xffff0000, v14
	v_lshlrev_b32_e32 v14, 16, v15
	v_and_b32_e32 v15, 0xffff0000, v15
	v_pk_mul_f32 v[14:15], v[0:1], v[14:15] op_sel_hi:[0,1]
	v_pk_mul_f32 v[14:15], v[14:15], v[68:69]
	v_pk_mul_f32 v[18:19], v[0:1], v[18:19] op_sel_hi:[0,1]
	v_cvt_pk_bf16_f32 v117, v14, v15
	v_lshlrev_b32_e32 v14, 16, v16
	v_and_b32_e32 v15, 0xffff0000, v16
	v_pk_mul_f32 v[14:15], v[0:1], v[14:15] op_sel_hi:[0,1]
	v_pk_mul_f32 v[14:15], v[14:15], v[58:59]
	v_pk_mul_f32 v[18:19], v[18:19], v[66:67]
	v_cvt_pk_bf16_f32 v118, v14, v15
	v_lshlrev_b32_e32 v14, 16, v17
	v_and_b32_e32 v15, 0xffff0000, v17
	v_pk_mul_f32 v[14:15], v[0:1], v[14:15] op_sel_hi:[0,1]
	v_pk_mul_f32 v[14:15], v[14:15], v[60:61]
	v_cvt_pk_bf16_f32 v116, v18, v19
	v_cvt_pk_bf16_f32 v119, v14, v15
	v_lshlrev_b32_e32 v14, 16, v10
	v_and_b32_e32 v15, 0xffff0000, v10
	v_lshlrev_b32_e32 v10, 16, v11
	v_and_b32_e32 v11, 0xffff0000, v11
	v_pk_mul_f32 v[10:11], v[0:1], v[10:11] op_sel_hi:[0,1]
	v_pk_mul_f32 v[10:11], v[10:11], v[56:57]
	v_pk_mul_f32 v[14:15], v[0:1], v[14:15] op_sel_hi:[0,1]
	v_cvt_pk_bf16_f32 v121, v10, v11
	v_lshlrev_b32_e32 v10, 16, v12
	v_and_b32_e32 v11, 0xffff0000, v12
	v_pk_mul_f32 v[10:11], v[0:1], v[10:11] op_sel_hi:[0,1]
	v_pk_mul_f32 v[10:11], v[10:11], v[50:51]
	v_mov_b32_e32 v50, 0
	v_cvt_pk_bf16_f32 v122, v10, v11
	v_lshlrev_b32_e32 v10, 16, v13
	v_and_b32_e32 v11, 0xffff0000, v13
	v_pk_mul_f32 v[10:11], v[0:1], v[10:11] op_sel_hi:[0,1]
	v_pk_mul_f32 v[10:11], v[10:11], v[52:53]
	v_pk_mul_f32 v[14:15], v[14:15], v[54:55]
	v_cvt_pk_bf16_f32 v123, v10, v11
	v_lshlrev_b32_e32 v10, 16, v6
	v_and_b32_e32 v11, 0xffff0000, v6
	v_lshlrev_b32_e32 v6, 16, v7
	v_and_b32_e32 v7, 0xffff0000, v7
	v_pk_mul_f32 v[6:7], v[0:1], v[6:7] op_sel_hi:[0,1]
	v_pk_mul_f32 v[6:7], v[6:7], v[48:49]
	v_pk_mul_f32 v[10:11], v[0:1], v[10:11] op_sel_hi:[0,1]
	v_cvt_pk_bf16_f32 v125, v6, v7
	v_lshlrev_b32_e32 v6, 16, v8
	v_and_b32_e32 v7, 0xffff0000, v8
	v_pk_mul_f32 v[6:7], v[0:1], v[6:7] op_sel_hi:[0,1]
	v_pk_mul_f32 v[6:7], v[6:7], v[42:43]
	v_pk_mul_f32 v[10:11], v[10:11], v[46:47]
	v_cvt_pk_bf16_f32 v126, v6, v7
	v_lshlrev_b32_e32 v6, 16, v9
	v_and_b32_e32 v7, 0xffff0000, v9
	v_pk_mul_f32 v[6:7], v[0:1], v[6:7] op_sel_hi:[0,1]
	v_pk_mul_f32 v[6:7], v[6:7], v[44:45]
	v_mov_b32_e32 v51, v50
	v_cvt_pk_bf16_f32 v127, v6, v7
	v_lshlrev_b32_e32 v6, 16, v2
	v_and_b32_e32 v7, 0xffff0000, v2
	v_lshlrev_b32_e32 v2, 16, v3
	v_and_b32_e32 v3, 0xffff0000, v3
	v_pk_mul_f32 v[2:3], v[0:1], v[2:3] op_sel_hi:[0,1]
	v_pk_mul_f32 v[2:3], v[2:3], v[40:41]
	v_pk_mul_f32 v[6:7], v[0:1], v[6:7] op_sel_hi:[0,1]
	v_cvt_pk_bf16_f32 v129, v2, v3
	v_lshlrev_b32_e32 v2, 16, v4
	v_and_b32_e32 v3, 0xffff0000, v4
	v_pk_mul_f32 v[2:3], v[0:1], v[2:3] op_sel_hi:[0,1]
	v_pk_mul_f32 v[2:3], v[2:3], v[34:35]
	v_pk_mul_f32 v[6:7], v[6:7], v[38:39]
	v_cvt_pk_bf16_f32 v130, v2, v3
	v_lshlrev_b32_e32 v2, 16, v5
	v_and_b32_e32 v3, 0xffff0000, v5
	v_pk_mul_f32 v[2:3], v[0:1], v[2:3] op_sel_hi:[0,1]
	v_pk_mul_f32 v[2:3], v[2:3], v[36:37]
	v_cvt_pk_bf16_f32 v120, v14, v15
	v_cvt_pk_bf16_f32 v131, v2, v3
	v_lshl_or_b32 v2, v99, 8, v132
	v_lshl_or_b32 v3, v133, 4, v2
	v_add_u32_e32 v2, 0x400, v2
	v_or3_b32 v67, v135, v134, v2
	v_or3_b32 v223, v135, v64, v2
	v_or3_b32 v225, v135, v65, v2
	v_or3_b32 v227, v135, v136, v2
	v_lshlrev_b32_e32 v2, 2, v211
	v_sub_u32_e32 v2, s0, v2
	s_lshl_b32 s0, s22, 7
	v_subrev_u32_e32 v2, s0, v2
	s_lshl_b32 s0, s98, 10
	v_cvt_pk_bf16_f32 v124, v10, v11
	v_cvt_pk_bf16_f32 v128, v6, v7
	v_or_b32_e32 v0, v3, v134
	v_or_b32_e32 v222, v3, v64
	v_or_b32_e32 v224, v3, v65
	v_or_b32_e32 v226, v3, v136
	v_subrev_u32_e32 v229, s0, v2
	v_mov_b32_e32 v52, v50
	v_mov_b32_e32 v53, v50
	v_mov_b32_e32 v54, v50
	v_mov_b32_e32 v55, v50
	v_mov_b32_e32 v56, v50
	v_mov_b32_e32 v57, v50
	v_mov_b32_e32 v58, v50
	v_mov_b32_e32 v59, v50
	v_mov_b32_e32 v60, v50
	v_mov_b32_e32 v61, v50
	v_mov_b32_e32 v62, v50
	v_mov_b32_e32 v63, v50
	v_mov_b32_e32 v64, v50
	v_mov_b32_e32 v65, v50
	v_mov_b64_e32 v[34:35], v[50:51]
	v_mov_b64_e32 v[18:19], v[50:51]
	v_mov_b64_e32 v[2:3], v[50:51]
	s_add_i32 s31, s31, 4
	s_add_i32 s34, s13, -4
	s_add_i32 s0, s62, 0x80
	v_mov_b32_e32 v230, 0xf149f2ca
	v_mov_b64_e32 v[36:37], v[52:53]
	v_mov_b64_e32 v[38:39], v[54:55]
	v_mov_b64_e32 v[40:41], v[56:57]
	v_mov_b64_e32 v[42:43], v[58:59]
	v_mov_b64_e32 v[44:45], v[60:61]
	v_mov_b64_e32 v[46:47], v[62:63]
	v_mov_b64_e32 v[48:49], v[64:65]
	v_mov_b64_e32 v[20:21], v[52:53]
	v_mov_b64_e32 v[22:23], v[54:55]
	v_mov_b64_e32 v[24:25], v[56:57]
	v_mov_b64_e32 v[26:27], v[58:59]
	v_mov_b64_e32 v[28:29], v[60:61]
	v_mov_b64_e32 v[30:31], v[62:63]
	v_mov_b64_e32 v[32:33], v[64:65]
	v_mov_b64_e32 v[4:5], v[52:53]
	v_mov_b64_e32 v[6:7], v[54:55]
	v_mov_b64_e32 v[8:9], v[56:57]
	v_mov_b64_e32 v[10:11], v[58:59]
	v_mov_b64_e32 v[12:13], v[60:61]
	v_mov_b64_e32 v[14:15], v[62:63]
	v_mov_b64_e32 v[16:17], v[64:65]
	v_mov_b32_e32 v66, v50
	s_mov_b32 s35, 0
	.p2alignl 6, 3212836864

.LBB0_295:
	s_lshl_b32 s8, s37, 15
	s_add_i32 s8, s8, 0
	v_add_u32_e32 v84, s8, v214
	v_add_u32_e32 v86, s8, v216
	v_add_u32_e32 v88, s8, v218
	v_add_u32_e32 v90, s8, v220
	v_add_u32_e32 v85, s8, v215
	ds_read_b128 v[68:71], v84
	ds_read_b128 v[72:75], v85
	v_add_u32_e32 v87, s8, v217
	ds_read_b128 v[76:79], v86
	ds_read_b128 v[80:83], v87
	v_add_u32_e32 v89, s8, v219
	ds_read_b128 v[132:135], v88
	ds_read_b128 v[136:139], v89
	v_add_u32_e32 v91, s8, v221
	ds_read_b128 v[140:143], v90
	ds_read_b128 v[164:167], v91
	s_setprio 1
	ds_read_b128 v[144:147], v84 offset:8192
	ds_read_b128 v[148:151], v85 offset:8192
	ds_read_b128 v[152:155], v86 offset:8192
	ds_read_b128 v[156:159], v87 offset:8192
	ds_read_b128 v[160:163], v88 offset:8192
	ds_read_b128 v[168:171], v89 offset:8192
	ds_read_b128 v[172:175], v90 offset:8192
	ds_read_b128 v[176:179], v91 offset:8192
	s_waitcnt lgkmcnt(0)
	v_mfma_f32_32x32x16_bf16 v[84:99], v[68:71], v[100:103], 0
	v_add_u32_e32 v235, s8, v0
	v_add_u32_e32 v234, s8, v224
	v_add_u32_e32 v239, s8, v67
	v_add_u32_e32 v237, s8, v222
	v_add_u32_e32 v238, s8, v223
	v_add_u32_e32 v236, s8, v225
	v_add_u32_e32 v232, s8, v226
	v_mfma_f32_32x32x16_bf16 v[84:99], v[72:75], v[104:107], v[84:99]
	v_add_u32_e32 v233, s8, v227
	v_mfma_f32_32x32x16_bf16 v[84:99], v[76:79], v[108:111], v[84:99]
	v_mfma_f32_32x32x16_bf16 v[84:99], v[80:83], v[112:115], v[84:99]
	v_mfma_f32_32x32x16_bf16 v[68:83], v[144:147], v[100:103], 0
	v_mfma_f32_32x32x16_bf16 v[68:83], v[148:151], v[104:107], v[68:83]
	v_mfma_f32_32x32x16_bf16 v[68:83], v[152:155], v[108:111], v[68:83]
	v_mfma_f32_32x32x16_bf16 v[68:83], v[156:159], v[112:115], v[68:83]
	v_mfma_f32_32x32x16_bf16 v[84:99], v[132:135], v[116:119], v[84:99]
	v_mfma_f32_32x32x16_bf16 v[68:83], v[160:163], v[116:119], v[68:83]
	v_mfma_f32_32x32x16_bf16 v[84:99], v[136:139], v[120:123], v[84:99]
	ds_read_b64_tr_b16 v[148:149], v235 offset:16384
	ds_read_b64_tr_b16 v[150:151], v239 offset:16384
	ds_read_b64_tr_b16 v[134:135], v239 offset:20480
	ds_read_b64_tr_b16 v[132:133], v235 offset:20480
	ds_read_b64_tr_b16 v[152:153], v237 offset:16384
	ds_read_b64_tr_b16 v[154:155], v238 offset:16384
	ds_read_b64_tr_b16 v[138:139], v238 offset:20480
	ds_read_b64_tr_b16 v[136:137], v237 offset:20480
	v_mfma_f32_32x32x16_bf16 v[68:83], v[168:171], v[120:123], v[68:83]
	v_mfma_f32_32x32x16_bf16 v[84:99], v[140:143], v[124:127], v[84:99]
	ds_read_b64_tr_b16 v[156:157], v234 offset:16384
	ds_read_b64_tr_b16 v[158:159], v236 offset:16384
	ds_read_b64_tr_b16 v[142:143], v236 offset:20480
	ds_read_b64_tr_b16 v[140:141], v234 offset:20480
	ds_read_b64_tr_b16 v[160:161], v232 offset:16384
	ds_read_b64_tr_b16 v[162:163], v233 offset:16384
	ds_read_b64_tr_b16 v[146:147], v233 offset:20480
	ds_read_b64_tr_b16 v[144:145], v232 offset:20480
	v_mfma_f32_32x32x16_bf16 v[68:83], v[172:175], v[124:127], v[68:83]
	v_mfma_f32_32x32x16_bf16 v[68:83], v[176:179], v[128:131], v[68:83]
	v_mfma_f32_32x32x16_bf16 v[84:99], v[164:167], v[128:131], v[84:99]
	s_setprio 0
	ds_read_b128 v[176:179], v228
	ds_read_b128 v[172:175], v228 offset:16
	ds_read_b128 v[168:171], v228 offset:64
	ds_read_b128 v[164:167], v228 offset:80
	s_cmp_ge_i32 s1, s34
	s_cselect_b64 s[8:9], -1, 0
	s_mov_b64 s[18:19], -1
	s_and_b64 vcc, exec, s[8:9]
	v_add_u32_e32 v231, v228, v229
	s_cbranch_vccz .LBB0_297
	v_add_u32_e32 v204, 0x10fc, v231
	ds_read2_b32 v[202:203], v204 offset1:1
	ds_read2_b32 v[200:201], v204 offset0:2 offset1:3
	ds_read2_b32 v[196:197], v204 offset0:4 offset1:5
	ds_read2_b32 v[192:193], v204 offset0:6 offset1:7
	ds_read2_b32 v[198:199], v204 offset0:16 offset1:17
	ds_read2_b32 v[194:195], v204 offset0:18 offset1:19
	ds_read2_b32 v[190:191], v204 offset0:20 offset1:21
	ds_read2_b32 v[188:189], v204 offset0:22 offset1:23
	s_mov_b64 s[18:19], 0
.LBB0_297:
	s_andn2_b64 vcc, exec, s[18:19]
	s_cbranch_vccnz .LBB0_299
	s_add_i32 s1, 0, 0x18c00
	s_waitcnt lgkmcnt(0)
	v_mov_b32_e32 v188, s1
	ds_read_b32 v205, v188
	s_waitcnt lgkmcnt(0)
	s_waitcnt lgkmcnt(0)
	v_fma_f32 v202, v84, v176, v205
	v_fma_f32 v196, v88, v172, v205
	v_fma_f32 v203, v85, v177, v205
	v_fma_f32 v197, v89, v173, v205
	v_fma_f32 v200, v86, v178, v205
	v_fma_f32 v201, v87, v179, v205
	v_fma_f32 v198, v92, v168, v205
	v_fma_f32 v199, v93, v169, v205
	v_fma_f32 v192, v90, v174, v205
	v_fma_f32 v193, v91, v175, v205
	v_max3_f32 v84, v202, v203, v200
	v_max3_f32 v85, v201, v196, v197
	v_fma_f32 v190, v96, v164, v205
	v_fma_f32 v191, v97, v165, v205
	v_fma_f32 v194, v94, v170, v205
	v_fma_f32 v188, v98, v166, v205
	v_fma_f32 v195, v95, v171, v205
	v_fma_f32 v189, v99, v167, v205
	s_branch .Lm1f_a

.Lm1f_a:
	v_max3_f32 v84, v84, v192, v193
	v_max3_f32 v85, v85, v198, v199
	v_max3_f32 v84, v84, v194, v195
	v_max3_f32 v85, v85, v190, v191
	v_max_f32_e32 v86, v188, v189
	v_max3_f32 v84, v84, v85, v86
	v_mov_b32_e32 v85, v84
	v_mov_b32_e32 v86, v84
	s_nop 1
	v_permlane32_swap_b32_e32 v85, v86
	v_cndmask_b32_e64 v85, v85, v86, s[6:7]
	v_max_f32_e32 v85, v85, v85
	v_max_f32_e32 v84, v84, v85
	v_add_f32_e32 v85, 0x41000000, v230
	v_cmp_gt_f32_e32 vcc, v84, v85
	s_cbranch_vccz .LBB0_301
	v_max_f32_e32 v84, v84, v84
	v_max_f32_e32 v85, v230, v230
	v_max_f32_e32 v85, v85, v84
	v_sub_f32_e32 v84, v230, v85
	v_exp_f32_e32 v84, v84
	v_mov_b32_e32 v230, v85
	v_pk_mul_f32 v[64:65], v[64:65], v[84:85] op_sel_hi:[1,0]
	v_pk_mul_f32 v[62:63], v[62:63], v[84:85] op_sel_hi:[1,0]
	v_pk_mul_f32 v[60:61], v[60:61], v[84:85] op_sel_hi:[1,0]
	v_pk_mul_f32 v[58:59], v[58:59], v[84:85] op_sel_hi:[1,0]
	v_pk_mul_f32 v[56:57], v[56:57], v[84:85] op_sel_hi:[1,0]
	v_pk_mul_f32 v[54:55], v[54:55], v[84:85] op_sel_hi:[1,0]
	v_pk_mul_f32 v[52:53], v[52:53], v[84:85] op_sel_hi:[1,0]
	v_pk_mul_f32 v[50:51], v[50:51], v[84:85] op_sel_hi:[1,0]
	v_pk_mul_f32 v[48:49], v[48:49], v[84:85] op_sel_hi:[1,0]
	v_pk_mul_f32 v[46:47], v[46:47], v[84:85] op_sel_hi:[1,0]
	v_pk_mul_f32 v[44:45], v[44:45], v[84:85] op_sel_hi:[1,0]
	v_pk_mul_f32 v[42:43], v[42:43], v[84:85] op_sel_hi:[1,0]
	v_pk_mul_f32 v[40:41], v[40:41], v[84:85] op_sel_hi:[1,0]
	v_pk_mul_f32 v[38:39], v[38:39], v[84:85] op_sel_hi:[1,0]
	v_pk_mul_f32 v[36:37], v[36:37], v[84:85] op_sel_hi:[1,0]
	v_pk_mul_f32 v[34:35], v[34:35], v[84:85] op_sel_hi:[1,0]
	v_pk_mul_f32 v[32:33], v[32:33], v[84:85] op_sel_hi:[1,0]
	v_pk_mul_f32 v[30:31], v[30:31], v[84:85] op_sel_hi:[1,0]
	v_pk_mul_f32 v[28:29], v[28:29], v[84:85] op_sel_hi:[1,0]
	v_pk_mul_f32 v[26:27], v[26:27], v[84:85] op_sel_hi:[1,0]
	v_pk_mul_f32 v[24:25], v[24:25], v[84:85] op_sel_hi:[1,0]
	v_pk_mul_f32 v[22:23], v[22:23], v[84:85] op_sel_hi:[1,0]
	v_pk_mul_f32 v[20:21], v[20:21], v[84:85] op_sel_hi:[1,0]
	v_pk_mul_f32 v[18:19], v[18:19], v[84:85] op_sel_hi:[1,0]
	v_pk_mul_f32 v[16:17], v[16:17], v[84:85] op_sel_hi:[1,0]
	v_pk_mul_f32 v[14:15], v[14:15], v[84:85] op_sel_hi:[1,0]
	v_pk_mul_f32 v[12:13], v[12:13], v[84:85] op_sel_hi:[1,0]
	v_pk_mul_f32 v[10:11], v[10:11], v[84:85] op_sel_hi:[1,0]
	v_pk_mul_f32 v[8:9], v[8:9], v[84:85] op_sel_hi:[1,0]
	v_pk_mul_f32 v[6:7], v[6:7], v[84:85] op_sel_hi:[1,0]
	v_pk_mul_f32 v[4:5], v[4:5], v[84:85] op_sel_hi:[1,0]
	v_pk_mul_f32 v[2:3], v[2:3], v[84:85] op_sel_hi:[1,0]
	v_mul_f32_e32 v66, v66, v84
.LBB0_301:
	v_sub_f32_e32 v84, v202, v230
	v_exp_f32_e32 v202, v84
	v_sub_f32_e32 v84, v203, v230
	v_exp_f32_e32 v203, v84
	v_sub_f32_e32 v84, v200, v230
	v_exp_f32_e32 v200, v84
	v_sub_f32_e32 v84, v201, v230
	v_exp_f32_e32 v201, v84
	v_sub_f32_e32 v84, v196, v230
	v_exp_f32_e32 v196, v84
	v_sub_f32_e32 v84, v197, v230
	v_exp_f32_e32 v197, v84
	v_sub_f32_e32 v84, v192, v230
	v_exp_f32_e32 v192, v84
	v_sub_f32_e32 v84, v193, v230
	v_exp_f32_e32 v193, v84
	v_sub_f32_e32 v84, v198, v230
	v_exp_f32_e32 v198, v84
	v_sub_f32_e32 v84, v199, v230
	v_exp_f32_e32 v199, v84
	v_sub_f32_e32 v84, v194, v230
	v_exp_f32_e32 v194, v84
	v_sub_f32_e32 v84, v195, v230
	v_exp_f32_e32 v195, v84
	v_sub_f32_e32 v84, v190, v230
	v_exp_f32_e32 v190, v84
	v_sub_f32_e32 v84, v191, v230
	v_exp_f32_e32 v191, v84
	v_sub_f32_e32 v84, v188, v230
	v_exp_f32_e32 v188, v84
	v_sub_f32_e32 v84, v189, v230
	v_exp_f32_e32 v189, v84
	s_setprio 1
	v_cvt_pk_bf16_f32 v84, v202, v203
	v_cvt_pk_bf16_f32 v85, v200, v201
	v_cvt_pk_bf16_f32 v86, v196, v197
	v_cvt_pk_bf16_f32 v87, v192, v193
	s_nop 1
	v_mfma_f32_32x32x16_bf16 v[50:65], v[148:151], v[84:87], v[50:65]
	v_mfma_f32_32x32x16_bf16 v[34:49], v[152:155], v[84:87], v[34:49]
	v_mfma_f32_32x32x16_bf16 v[18:33], v[156:159], v[84:87], v[18:33]
	v_mfma_f32_32x32x16_bf16 v[2:17], v[160:163], v[84:87], v[2:17]
	v_cvt_pk_bf16_f32 v84, v198, v199
	v_cvt_pk_bf16_f32 v85, v194, v195
	v_cvt_pk_bf16_f32 v86, v190, v191
	v_cvt_pk_bf16_f32 v87, v188, v189
	s_nop 1
	v_mfma_f32_32x32x16_bf16 v[50:65], v[132:135], v[84:87], v[50:65]
	v_mfma_f32_32x32x16_bf16 v[34:49], v[136:139], v[84:87], v[34:49]
	v_mfma_f32_32x32x16_bf16 v[18:33], v[140:143], v[84:87], v[18:33]
	v_mfma_f32_32x32x16_bf16 v[2:17], v[144:147], v[84:87], v[2:17]
	s_setprio 0
	ds_read_b64_tr_b16 v[92:93], v235 offset:24576
	ds_read_b64_tr_b16 v[94:95], v239 offset:24576
	ds_read_b64_tr_b16 v[86:87], v239 offset:28672
	ds_read_b64_tr_b16 v[84:85], v235 offset:28672
	ds_read_b64_tr_b16 v[136:137], v237 offset:24576
	ds_read_b64_tr_b16 v[138:139], v238 offset:24576
	ds_read_b64_tr_b16 v[90:91], v238 offset:28672
	ds_read_b64_tr_b16 v[88:89], v237 offset:28672
	ds_read_b64_tr_b16 v[140:141], v234 offset:24576
	ds_read_b64_tr_b16 v[142:143], v236 offset:24576
	ds_read_b64_tr_b16 v[98:99], v236 offset:28672
	ds_read_b64_tr_b16 v[96:97], v234 offset:28672
	ds_read_b64_tr_b16 v[144:145], v232 offset:24576
	ds_read_b64_tr_b16 v[146:147], v233 offset:24576
	ds_read_b64_tr_b16 v[134:135], v233 offset:28672
	ds_read_b64_tr_b16 v[132:133], v232 offset:28672
	ds_read_b128 v[160:163], v228 offset:128
	ds_read_b128 v[156:159], v228 offset:144
	ds_read_b128 v[152:155], v228 offset:192
	ds_read_b128 v[148:151], v228 offset:208
	s_mov_b64 s[18:19], -1
	s_and_b64 vcc, exec, s[8:9]
	s_cbranch_vccz .LBB0_303
	v_add_u32_e32 v204, 0x117c, v231
	ds_read2_b32 v[178:179], v204 offset1:1
	ds_read2_b32 v[176:177], v204 offset0:2 offset1:3
	ds_read2_b32 v[174:175], v204 offset0:4 offset1:5
	ds_read2_b32 v[172:173], v204 offset0:6 offset1:7
	ds_read2_b32 v[170:171], v204 offset0:16 offset1:17
	ds_read2_b32 v[168:169], v204 offset0:18 offset1:19
	ds_read2_b32 v[166:167], v204 offset0:20 offset1:21
	ds_read2_b32 v[164:165], v204 offset0:22 offset1:23
	s_mov_b64 s[18:19], 0
.LBB0_303:
	s_andn2_b64 vcc, exec, s[18:19]
	s_cbranch_vccnz .LBB0_305
	s_add_i32 s1, 0, 0x18c00
	s_waitcnt lgkmcnt(0)
	v_mov_b32_e32 v164, s1
	ds_read_b32 v205, v164
	s_waitcnt lgkmcnt(0)
	v_add_f32_e32 v202, 0, v202
	v_add_f32_e32 v202, v203, v202
	v_add_f32_e32 v200, v200, v202
	v_add_f32_e32 v200, v201, v200
	v_add_f32_e32 v196, v196, v200
	v_add_f32_e32 v196, v197, v196
	v_add_f32_e32 v192, v192, v196
	s_waitcnt lgkmcnt(0)
	v_fma_f32 v178, v68, v160, v205
	v_fma_f32 v174, v72, v156, v205
	v_fma_f32 v179, v69, v161, v205
	v_fma_f32 v175, v73, v157, v205
	v_fma_f32 v176, v70, v162, v205
	v_fma_f32 v177, v71, v163, v205
	v_add_f32_e32 v192, v193, v192
	v_fma_f32 v170, v76, v152, v205
	v_fma_f32 v171, v77, v153, v205
	v_fma_f32 v172, v74, v158, v205
	v_fma_f32 v173, v75, v159, v205
	v_max3_f32 v68, v178, v179, v176
	v_max3_f32 v69, v177, v174, v175
	v_add_f32_e32 v192, v198, v192
	v_fma_f32 v166, v80, v148, v205
	v_fma_f32 v167, v81, v149, v205
	v_fma_f32 v168, v78, v154, v205
	v_fma_f32 v164, v82, v150, v205
	v_fma_f32 v169, v79, v155, v205
	v_fma_f32 v165, v83, v151, v205
	s_branch .Lm1f_b

.Lm1f_b:
	v_max3_f32 v68, v68, v172, v173
	v_max3_f32 v69, v69, v170, v171
	v_add_f32_e32 v192, v199, v192
	v_max3_f32 v68, v68, v168, v169
	v_max3_f32 v69, v69, v166, v167
	v_max_f32_e32 v70, v164, v165
	v_add_f32_e32 v192, v194, v192
	v_max3_f32 v68, v68, v69, v70
	v_add_f32_e32 v192, v195, v192
	v_mov_b32_e32 v69, v68
	v_mov_b32_e32 v70, v68
	v_add_f32_e32 v190, v190, v192
	s_nop 0
	v_permlane32_swap_b32_e32 v69, v70
	v_add_f32_e32 v190, v191, v190
	v_cndmask_b32_e64 v69, v69, v70, s[6:7]
	v_add_f32_e32 v188, v188, v190
	v_max_f32_e32 v69, v69, v69
	v_add_f32_e32 v188, v189, v188
	v_max_f32_e32 v68, v68, v69
	v_add_f32_e32 v69, 0x41000000, v230
	v_add_f32_e32 v66, v66, v188
	v_cmp_gt_f32_e32 vcc, v68, v69
	s_cbranch_vccz .LBB0_307
	v_max_f32_e32 v68, v68, v68
	v_max_f32_e32 v69, v230, v230
	v_max_f32_e32 v69, v69, v68
	v_sub_f32_e32 v68, v230, v69
	v_exp_f32_e32 v68, v68
	v_mov_b32_e32 v230, v69
	v_pk_mul_f32 v[64:65], v[64:65], v[68:69] op_sel_hi:[1,0]
	v_pk_mul_f32 v[62:63], v[62:63], v[68:69] op_sel_hi:[1,0]
	v_pk_mul_f32 v[60:61], v[60:61], v[68:69] op_sel_hi:[1,0]
	v_pk_mul_f32 v[58:59], v[58:59], v[68:69] op_sel_hi:[1,0]
	v_pk_mul_f32 v[56:57], v[56:57], v[68:69] op_sel_hi:[1,0]
	v_pk_mul_f32 v[54:55], v[54:55], v[68:69] op_sel_hi:[1,0]
	v_pk_mul_f32 v[52:53], v[52:53], v[68:69] op_sel_hi:[1,0]
	v_pk_mul_f32 v[50:51], v[50:51], v[68:69] op_sel_hi:[1,0]
	v_pk_mul_f32 v[48:49], v[48:49], v[68:69] op_sel_hi:[1,0]
	v_pk_mul_f32 v[46:47], v[46:47], v[68:69] op_sel_hi:[1,0]
	v_pk_mul_f32 v[44:45], v[44:45], v[68:69] op_sel_hi:[1,0]
	v_pk_mul_f32 v[42:43], v[42:43], v[68:69] op_sel_hi:[1,0]
	v_pk_mul_f32 v[40:41], v[40:41], v[68:69] op_sel_hi:[1,0]
	v_pk_mul_f32 v[38:39], v[38:39], v[68:69] op_sel_hi:[1,0]
	v_pk_mul_f32 v[36:37], v[36:37], v[68:69] op_sel_hi:[1,0]
	v_pk_mul_f32 v[34:35], v[34:35], v[68:69] op_sel_hi:[1,0]
	v_pk_mul_f32 v[32:33], v[32:33], v[68:69] op_sel_hi:[1,0]
	v_pk_mul_f32 v[30:31], v[30:31], v[68:69] op_sel_hi:[1,0]
	v_pk_mul_f32 v[28:29], v[28:29], v[68:69] op_sel_hi:[1,0]
	v_pk_mul_f32 v[26:27], v[26:27], v[68:69] op_sel_hi:[1,0]
	v_pk_mul_f32 v[24:25], v[24:25], v[68:69] op_sel_hi:[1,0]
	v_pk_mul_f32 v[22:23], v[22:23], v[68:69] op_sel_hi:[1,0]
	v_pk_mul_f32 v[20:21], v[20:21], v[68:69] op_sel_hi:[1,0]
	v_pk_mul_f32 v[18:19], v[18:19], v[68:69] op_sel_hi:[1,0]
	v_pk_mul_f32 v[16:17], v[16:17], v[68:69] op_sel_hi:[1,0]
	v_pk_mul_f32 v[14:15], v[14:15], v[68:69] op_sel_hi:[1,0]
	v_pk_mul_f32 v[12:13], v[12:13], v[68:69] op_sel_hi:[1,0]
	v_pk_mul_f32 v[10:11], v[10:11], v[68:69] op_sel_hi:[1,0]
	v_pk_mul_f32 v[8:9], v[8:9], v[68:69] op_sel_hi:[1,0]
	v_pk_mul_f32 v[6:7], v[6:7], v[68:69] op_sel_hi:[1,0]
	v_pk_mul_f32 v[4:5], v[4:5], v[68:69] op_sel_hi:[1,0]
	v_pk_mul_f32 v[2:3], v[2:3], v[68:69] op_sel_hi:[1,0]
	v_mul_f32_e32 v66, v66, v68

.LBB0_321:
	s_or_b64 exec, exec, s[6:7]
	v_and_b32_e32 v0, 16, v190
	v_and_b32_e32 v7, 3, v190
	v_or3_b32 v0, v6, v0, v7
	v_lshlrev_b32_e32 v7, 8, v0
	v_lshlrev_b32_e32 v0, 2, v0
	v_and_b32_e32 v0, 12, v0
	v_lshrrev_b32_e32 v6, 2, v6
	v_bitop3_b32 v8, v0, v5, v6 bitop3:0x36
	v_lshl_or_b32 v195, v8, 4, v7
	v_or_b32_e32 v8, 2, v5
	v_bitop3_b32 v8, v0, v8, v6 bitop3:0x36
	v_lshl_or_b32 v196, v8, 4, v7
	v_or_b32_e32 v8, 4, v5
	v_bitop3_b32 v8, v0, v8, v6 bitop3:0x36
	v_lshl_or_b32 v197, v8, 4, v7
	v_or_b32_e32 v8, 6, v5
	v_bitop3_b32 v8, v0, v8, v6 bitop3:0x36
	v_lshl_or_b32 v198, v8, 4, v7
	v_or_b32_e32 v8, 8, v5
	v_bitop3_b32 v8, v0, v8, v6 bitop3:0x36
	v_lshl_or_b32 v199, v8, 4, v7
	v_or_b32_e32 v8, 10, v5
	v_bitop3_b32 v8, v0, v8, v6 bitop3:0x36
	v_lshl_or_b32 v200, v8, 4, v7
	v_or_b32_e32 v8, 12, v5
	v_bitop3_b32 v8, v0, v8, v6 bitop3:0x36
	v_lshl_or_b32 v201, v8, 4, v7
	v_or_b32_e32 v8, 14, v5
	v_bitop3_b32 v0, v0, v8, v6 bitop3:0x36
	v_lshl_or_b32 v202, v0, 4, v7
	v_lshlrev_b32_e32 v7, 1, v191
	s_lshl_b32 s2, s56, 2
	s_and_b32 s12, s20, 1
	v_lshlrev_b32_e32 v194, 3, v5
	v_lshrrev_b32_e32 v0, 2, v192
	v_and_b32_e32 v7, 2, v7
	v_bfe_u32 v8, v190, 1, 1
	v_lshlrev_b32_e32 v5, 1, v5
	v_lshlrev_b32_e32 v9, 3, v190
	s_add_i32 s46, s2, 0
	s_mov_b32 s99, s63
	s_lshl_b32 s13, s21, 21
	s_lshl_b32 s12, s12, 23
	v_or_b32_e32 v6, v194, v0
	v_and_b32_e32 v9, 8, v9
	v_bitop3_b32 v10, v7, v5, v8 bitop3:0x36
	v_or_b32_e32 v5, 1, v5
	s_add_i32 s46, s46, 0x19400
	s_or_b32 s47, s16, 2
	s_or_b32 s48, s62, 30
	s_lshl_b64 s[2:3], s[98:99], 16
	s_add_i32 s50, s18, 0xff
	s_addk_i32 s17, 0xff20
	s_or_b32 s12, s12, s13
	v_lshlrev_b32_e32 v0, 6, v0
	v_bitop3_b32 v5, v7, v5, v8 bitop3:0x36
	v_cmp_gt_u32_e64 s[6:7], 32, v4
	v_cmp_eq_u32_e64 s[8:9], 0, v4
	v_lshl_or_b32 v4, v6, 8, v9
	s_add_u32 s12, s53, s12
	v_lshlrev_b32_e32 v5, 4, v5
	v_xor_b32_e32 v7, 64, v0
	v_xor_b32_e32 v8, 0x80, v0
	v_xor_b32_e32 v11, 0xc0, v0
	v_lshl_or_b32 v6, v10, 4, v4
	v_add_u32_e32 v4, 0x400, v4
	v_lshlrev_b32_e32 v224, 7, v191
	s_addc_u32 s13, s65, 0
	v_or3_b32 v226, v5, v0, v4
	v_or3_b32 v228, v5, v7, v4
	v_or3_b32 v230, v5, v8, v4
	v_or3_b32 v232, v5, v11, v4
	v_lshl_or_b32 v4, s56, 10, v224
	s_add_u32 s12, s12, s14
	v_or_b32_e32 v225, v6, v0
	v_or_b32_e32 v0, v4, v3
	s_addc_u32 s13, s13, s15
	s_movk_i32 s14, 0x200
	v_lshl_add_u64 v[172:173], v[0:1], 1, s[12:13]
	v_or3_b32 v0, v4, v2, s14
	v_mov_b32_e32 v14, v1
	v_mov_b32_e32 v15, v1
	v_or_b32_e32 v227, v6, v7
	v_or_b32_e32 v229, v6, v8
	v_or_b32_e32 v231, v6, v11
	v_lshl_add_u64 v[174:175], v[0:1], 1, s[12:13]
	v_mov_b32_e32 v0, v1
	v_mov_b32_e32 v2, v1
	v_mov_b32_e32 v3, v1
	v_mov_b32_e32 v4, v1
	v_mov_b32_e32 v5, v1
	v_mov_b32_e32 v6, v1
	v_mov_b32_e32 v7, v1
	v_mov_b32_e32 v8, v1
	v_mov_b32_e32 v9, v1
	v_mov_b32_e32 v10, v1
	v_mov_b32_e32 v11, v1
	v_mov_b32_e32 v12, v1
	v_mov_b32_e32 v13, v1
	v_mov_b64_e32 v[64:65], v[14:15]
	v_mov_b64_e32 v[48:49], v[14:15]
	v_mov_b64_e32 v[32:33], v[14:15]
	s_mov_b32 s60, 0xffff4000
	v_mov_b64_e32 v[62:63], v[12:13]
	v_mov_b64_e32 v[60:61], v[10:11]
	v_mov_b64_e32 v[58:59], v[8:9]
	v_mov_b64_e32 v[56:57], v[6:7]
	v_mov_b64_e32 v[54:55], v[4:5]
	v_mov_b64_e32 v[52:53], v[2:3]
	v_mov_b64_e32 v[50:51], v[0:1]
	v_mov_b64_e32 v[46:47], v[12:13]
	v_mov_b64_e32 v[44:45], v[10:11]
	v_mov_b64_e32 v[42:43], v[8:9]
	v_mov_b64_e32 v[40:41], v[6:7]
	v_mov_b64_e32 v[38:39], v[4:5]
	v_mov_b64_e32 v[36:37], v[2:3]
	v_mov_b64_e32 v[34:35], v[0:1]
	v_mov_b64_e32 v[30:31], v[12:13]
	v_mov_b64_e32 v[28:29], v[10:11]
	v_mov_b64_e32 v[26:27], v[8:9]
	v_mov_b64_e32 v[24:25], v[6:7]
	v_mov_b64_e32 v[22:23], v[4:5]
	v_mov_b64_e32 v[20:21], v[2:3]
	v_mov_b64_e32 v[18:19], v[0:1]
	v_mov_b64_e32 v[16:17], v[14:15]
	s_mov_b32 s49, 0
	v_or_b32_e32 v203, 1, v194
	v_or_b32_e32 v210, 2, v194
	v_or_b32_e32 v211, 3, v194
	v_or_b32_e32 v212, 4, v194
	v_or_b32_e32 v213, 5, v194
	v_or_b32_e32 v214, 6, v194
	v_or_b32_e32 v215, 7, v194
	v_or_b32_e32 v216, 16, v194
	v_or_b32_e32 v217, 17, v194
	v_or_b32_e32 v218, 18, v194
	v_or_b32_e32 v219, 19, v194
	v_or_b32_e32 v220, 20, v194
	v_or_b32_e32 v221, 21, v194
	v_or_b32_e32 v222, 22, v194
	v_or_b32_e32 v223, 23, v194
	v_add_u32_e32 v233, s17, v193
	s_mov_b64 s[12:13], -1
	v_mov_b32_e32 v234, 1.0
	s_mov_b32 s61, -1
	v_mov_b64_e32 v[14:15], v[12:13]
	v_mov_b64_e32 v[12:13], v[10:11]
	v_mov_b64_e32 v[10:11], v[8:9]
	v_mov_b64_e32 v[8:9], v[6:7]
	v_mov_b64_e32 v[6:7], v[4:5]
	v_mov_b64_e32 v[4:5], v[2:3]
	v_mov_b64_e32 v[2:3], v[0:1]
	s_mov_b32 s14, 0
	s_mov_b32 s51, 0
	s_waitcnt vmcnt(0)
	.p2alignl 6, 3212836864

.LBB0_327:
	v_mul_f32_e32 v166, v166, v167
	v_mul_f32_e32 v93, v93, v166
	v_mul_f32_e32 v92, v92, v93
	v_mul_f32_e32 v91, v91, v92
	v_mul_f32_e32 v90, v90, v91
	v_mul_f32_e32 v89, v89, v90
	v_mul_f32_e32 v94, v187, v86
	v_mul_f32_e32 v95, v88, v89
	v_pk_mul_f32 v[90:91], v[168:169], v[90:91]
	v_mul_f32_e32 v161, v87, v94
	v_mul_f32_e32 v160, v84, v161
	v_mul_f32_e32 v85, v85, v160
	v_mul_f32_e32 v84, v82, v85
	v_pk_mul_f32 v[184:185], v[184:185], v[160:161]
	v_mul_f32_e32 v161, v83, v84
	v_mul_f32_e32 v160, v0, v161
	v_mov_b32_e32 v0, v160
	v_mov_b32_e32 v82, v160
	s_nop 1
	v_permlane32_swap_b32_e32 v0, v82
	v_mov_b32_e32 v86, v95
	v_mov_b32_e32 v88, v95
	v_cndmask_b32_e64 v168, v0, v82, s[6:7]
	s_nop 0
	v_permlane32_swap_b32_e32 v86, v88
	v_mul_f32_e32 v0, v95, v168
	v_cndmask_b32_e64 v170, v86, v88, s[6:7]
	v_cndmask_b32_e64 v0, v95, v0, s[6:7]
	v_cndmask_b32_e64 v86, 1.0, v170, s[6:7]
	v_mov_b32_e32 v88, v95
	v_mul_f32_e32 v0, v0, v170
	v_mov_b32_e32 v186, v94
	v_mul_f32_e32 v86, v234, v86
	v_pk_mul_f32 v[88:89], v[188:189], v[88:89]
	v_pk_mul_f32 v[178:179], v[178:179], v[84:85]
	v_pk_mul_f32 v[82:83], v[176:177], v[160:161]
	v_mul_f32_e32 v0, v234, v0
	v_pk_mul_f32 v[92:93], v[164:165], v[92:93]
	v_pk_mul_f32 v[164:165], v[182:183], v[186:187]
	v_pk_mul_f32 v[162:163], v[166:167], v[162:163]
	v_pk_mul_f32 v[88:89], v[86:87], v[88:89] op_sel_hi:[0,1]
	v_pk_mul_f32 v[90:91], v[90:91], v[86:87] op_sel_hi:[1,0]
	v_pk_mul_f32 v[82:83], v[82:83], v[0:1] op_sel_hi:[1,0]
	v_pk_mul_f32 v[84:85], v[178:179], v[0:1] op_sel_hi:[1,0]
	v_pk_mul_f32 v[92:93], v[92:93], v[86:87] op_sel_hi:[1,0]
	v_pk_mul_f32 v[164:165], v[164:165], v[0:1] op_sel_hi:[1,0]
	v_pk_mul_f32 v[86:87], v[162:163], v[86:87] op_sel_hi:[1,0]
	v_pk_mul_f32 v[176:177], v[184:185], v[0:1] op_sel_hi:[1,0]
	s_setprio 1
	v_cvt_pk_bf16_f32 v82, v82, v83
	v_cvt_pk_bf16_f32 v83, v84, v85
	v_cvt_pk_bf16_f32 v84, v176, v177
	v_cvt_pk_bf16_f32 v85, v164, v165
	s_waitcnt lgkmcnt(0)
	s_nop 0
	v_mfma_f32_32x32x16_bf16 v[50:65], v[144:147], v[82:85], v[50:65]
	v_mfma_f32_32x32x16_bf16 v[34:49], v[148:151], v[82:85], v[34:49]
	v_mfma_f32_32x32x16_bf16 v[18:33], v[152:155], v[82:85], v[18:33]
	v_mfma_f32_32x32x16_bf16 v[2:17], v[156:159], v[82:85], v[2:17]
	v_cvt_pk_bf16_f32 v82, v88, v89
	v_cvt_pk_bf16_f32 v83, v90, v91
	v_cvt_pk_bf16_f32 v84, v92, v93
	v_cvt_pk_bf16_f32 v85, v86, v87
	s_nop 1
	v_mfma_f32_32x32x16_bf16 v[50:65], v[128:131], v[82:85], v[50:65]
	v_mfma_f32_32x32x16_bf16 v[34:49], v[132:135], v[82:85], v[34:49]
	v_mfma_f32_32x32x16_bf16 v[18:33], v[136:139], v[82:85], v[18:33]
	v_mfma_f32_32x32x16_bf16 v[2:17], v[140:143], v[82:85], v[2:17]
	s_setprio 0
	ds_read_b64_tr_b16 v[90:91], v238 offset:16384
	ds_read_b64_tr_b16 v[92:93], v242 offset:16384
	ds_read_b64_tr_b16 v[84:85], v242 offset:20480
	ds_read_b64_tr_b16 v[82:83], v238 offset:20480
	ds_read_b64_tr_b16 v[136:137], v240 offset:16384
	ds_read_b64_tr_b16 v[138:139], v241 offset:16384
	ds_read_b64_tr_b16 v[88:89], v241 offset:20480
	ds_read_b64_tr_b16 v[86:87], v240 offset:20480
	ds_read_b64_tr_b16 v[140:141], v237 offset:16384
	ds_read_b64_tr_b16 v[142:143], v239 offset:16384
	ds_read_b64_tr_b16 v[130:131], v239 offset:20480
	ds_read_b64_tr_b16 v[128:129], v237 offset:20480
	ds_read_b64_tr_b16 v[144:145], v235 offset:16384
	ds_read_b64_tr_b16 v[146:147], v236 offset:16384
	ds_read_b64_tr_b16 v[134:135], v236 offset:20480
	ds_read_b64_tr_b16 v[132:133], v235 offset:20480
	v_mul_f32_e32 v0, 0x3e0293ee, v66
	v_min_f32_e32 v0, 0x42700000, v0
	v_exp_f32_e32 v148, v0
	v_mul_f32_e32 v0, 0x3e0293ee, v67
	v_mul_f32_e32 v67, 0x3e0293ee, v68
	v_min_f32_e32 v67, 0x42700000, v67
	v_exp_f32_e32 v152, v67
	v_mul_f32_e32 v67, 0x3e0293ee, v69
	v_mul_f32_e32 v69, 0x3e0293ee, v70
	v_min_f32_e32 v69, 0x42700000, v69
	v_exp_f32_e32 v156, v69
	v_mul_f32_e32 v69, 0x3e0293ee, v71
	v_mul_f32_e32 v71, 0x3e0293ee, v72
	v_min_f32_e32 v71, 0x42700000, v71
	v_exp_f32_e32 v150, v71
	v_mul_f32_e32 v71, 0x3e0293ee, v73
	v_mul_f32_e32 v73, 0x3e0293ee, v74
	v_mul_f32_e32 v74, 0x3e0293ee, v76
	v_mul_f32_e32 v76, 0x3e0293ee, v78
	v_min_f32_e32 v73, 0x42700000, v73
	v_min_f32_e32 v74, 0x42700000, v74
	v_min_f32_e32 v76, 0x42700000, v76
	v_mul_f32_e32 v80, 0x3e0293ee, v80
	v_min_f32_e32 v0, 0x42700000, v0
	v_min_f32_e32 v67, 0x42700000, v67
	v_min_f32_e32 v69, 0x42700000, v69
	v_min_f32_e32 v71, 0x42700000, v71
	v_exp_f32_e32 v162, v73
	v_mul_f32_e32 v73, 0x3e0293ee, v75
	v_exp_f32_e32 v164, v74
	v_mul_f32_e32 v74, 0x3e0293ee, v77
	v_exp_f32_e32 v78, v76
	v_mul_f32_e32 v76, 0x3e0293ee, v79
	v_min_f32_e32 v80, 0x42700000, v80
	v_mul_f32_e32 v81, 0x3e0293ee, v81
	v_exp_f32_e32 v149, v0
	v_exp_f32_e32 v153, v67
	v_exp_f32_e32 v157, v69
	v_exp_f32_e32 v151, v71
	v_min_f32_e32 v73, 0x42700000, v73
	v_min_f32_e32 v74, 0x42700000, v74
	v_min_f32_e32 v76, 0x42700000, v76
	v_exp_f32_e32 v80, v80
	v_min_f32_e32 v81, 0x42700000, v81
	v_exp_f32_e32 v163, v73
	v_exp_f32_e32 v165, v74
	v_exp_f32_e32 v79, v76
	v_exp_f32_e32 v81, v81
	v_add_f32_e32 v66, 1.0, v149
	v_add_f32_e32 v68, 1.0, v153
	v_add_f32_e32 v70, 1.0, v157
	v_add_f32_e32 v72, 1.0, v151
	v_add_f32_e32 v94, 1.0, v80
	v_add_f32_e32 v0, 1.0, v148
	v_rcp_f32_e32 v67, v66
	v_add_f32_e32 v66, 1.0, v152
	v_rcp_f32_e32 v69, v68
	v_add_f32_e32 v68, 1.0, v156
	v_rcp_f32_e32 v71, v70
	v_add_f32_e32 v70, 1.0, v150
	v_rcp_f32_e32 v155, v72
	v_add_f32_e32 v72, 1.0, v162
	v_add_f32_e32 v73, 1.0, v163
	v_add_f32_e32 v74, 1.0, v164
	v_add_f32_e32 v75, 1.0, v165
	v_add_f32_e32 v76, 1.0, v78
	v_add_f32_e32 v77, 1.0, v79
	v_rcp_f32_e32 v158, v94
	v_add_f32_e32 v94, 1.0, v81
	v_rcp_f32_e32 v0, v0
	v_rcp_f32_e32 v66, v66
	v_rcp_f32_e32 v68, v68
	v_rcp_f32_e32 v70, v70
	v_rcp_f32_e32 v72, v72
	v_rcp_f32_e32 v73, v73
	v_rcp_f32_e32 v74, v74
	v_rcp_f32_e32 v75, v75
	v_rcp_f32_e32 v76, v76
	v_rcp_f32_e32 v77, v77
	v_rcp_f32_e32 v159, v94
	s_sub_i32 s12, s50, 32
	s_cmp_lt_i32 s12, s62
	s_cbranch_scc1 .LBB0_329
	v_add_u32_e32 v94, 32, v233
	v_cmp_lt_i32_e64 s[40:41], v222, v94
	v_cmp_lt_i32_e64 s[42:43], v223, v94
	v_cmp_lt_i32_e64 s[38:39], v221, v94
	s_or_b64 s[40:41], s[42:43], s[40:41]
	v_cmp_lt_i32_e64 s[36:37], v220, v94
	s_or_b64 s[38:39], s[40:41], s[38:39]
	v_cmp_lt_i32_e64 s[34:35], v219, v94
	s_or_b64 s[36:37], s[38:39], s[36:37]
	v_cmp_lt_i32_e64 s[30:31], v218, v94
	s_or_b64 s[34:35], s[36:37], s[34:35]
	v_cmp_lt_i32_e64 s[28:29], v217, v94
	s_or_b64 s[30:31], s[34:35], s[30:31]
	v_cmp_lt_i32_e64 s[26:27], v216, v94
	s_or_b64 s[28:29], s[30:31], s[28:29]
	v_cmp_lt_i32_e64 s[24:25], v215, v94
	s_or_b64 s[26:27], s[28:29], s[26:27]
	v_cmp_lt_i32_e64 s[22:23], v214, v94
	s_or_b64 s[24:25], s[26:27], s[24:25]
	v_cmp_lt_i32_e64 s[20:21], v213, v94
	s_or_b64 s[22:23], s[24:25], s[22:23]
	v_cmp_lt_i32_e64 s[18:19], v212, v94
	s_or_b64 s[20:21], s[22:23], s[20:21]
	v_cmp_lt_i32_e64 s[16:17], v211, v94
	s_or_b64 s[18:19], s[20:21], s[18:19]
	v_cmp_lt_i32_e64 s[14:15], v210, v94
	s_or_b64 s[16:17], s[18:19], s[16:17]
	v_cmp_lt_i32_e64 s[12:13], v203, v94
	s_or_b64 s[14:15], s[16:17], s[14:15]
	v_cmp_lt_i32_e32 vcc, v194, v94
	s_or_b64 s[12:13], s[14:15], s[12:13]
	s_or_b64 vcc, s[12:13], vcc
	v_cndmask_b32_e64 v159, 1.0, v159, s[42:43]
	v_cndmask_b32_e64 v158, 1.0, v158, s[40:41]
	v_cndmask_b32_e64 v77, 1.0, v77, s[38:39]
	v_cndmask_b32_e64 v76, 1.0, v76, s[36:37]
	v_cndmask_b32_e64 v75, 1.0, v75, s[34:35]
	v_cndmask_b32_e64 v74, 1.0, v74, s[30:31]
	v_cndmask_b32_e64 v73, 1.0, v73, s[28:29]
	v_cndmask_b32_e64 v72, 1.0, v72, s[26:27]
	v_cndmask_b32_e64 v155, 1.0, v155, s[24:25]
	v_cndmask_b32_e64 v70, 1.0, v70, s[22:23]
	v_cndmask_b32_e64 v71, 1.0, v71, s[20:21]
	v_cndmask_b32_e64 v68, 1.0, v68, s[18:19]
	v_cndmask_b32_e64 v69, 1.0, v69, s[16:17]
	v_cndmask_b32_e64 v66, 1.0, v66, s[14:15]
	v_cndmask_b32_e64 v67, 1.0, v67, s[12:13]
	v_cndmask_b32_e32 v0, 1.0, v0, vcc
	v_cndmask_b32_e64 v80, 0, v80, s[40:41]
	v_cndmask_b32_e64 v79, 0, v79, s[38:39]
	v_cndmask_b32_e64 v78, 0, v78, s[36:37]
	v_cndmask_b32_e64 v165, 0, v165, s[34:35]
	v_cndmask_b32_e64 v164, 0, v164, s[30:31]
	v_cndmask_b32_e64 v163, 0, v163, s[28:29]
	v_cndmask_b32_e64 v162, 0, v162, s[26:27]
	v_cndmask_b32_e64 v151, 0, v151, s[24:25]
	v_cndmask_b32_e64 v150, 0, v150, s[22:23]
	v_cndmask_b32_e64 v157, 0, v157, s[20:21]
	v_cndmask_b32_e64 v156, 0, v156, s[18:19]
	v_cndmask_b32_e64 v153, 0, v153, s[16:17]
	v_cndmask_b32_e64 v152, 0, v152, s[14:15]
	v_cndmask_b32_e64 v149, 0, v149, s[12:13]
	v_cndmask_b32_e32 v148, 0, v148, vcc
	v_cndmask_b32_e64 v81, 0, v81, s[42:43]
.LBB0_329:
	v_mul_f32_e32 v158, v158, v159
	v_mul_f32_e32 v77, v77, v158
	v_mul_f32_e32 v76, v76, v77
	v_mul_f32_e32 v94, v160, v95
	v_mul_f32_e32 v95, v168, v170
	v_mul_f32_e32 v75, v75, v76
	v_mul_f32_e32 v94, v95, v94
	v_mul_f32_e32 v74, v74, v75
	v_mul_f32_e32 v161, v234, v94
	v_mul_f32_e32 v73, v73, v74
	v_mul_f32_e32 v94, v155, v70
	v_mul_f32_e32 v95, v72, v73
	v_pk_mul_f32 v[74:75], v[164:165], v[74:75]
	v_mov_b32_e32 v70, v95
	v_mov_b32_e32 v72, v95
	s_nop 1
	v_permlane32_swap_b32_e32 v70, v72
	v_cndmask_b32_e64 v70, v70, v72, s[6:7]
	v_cndmask_b32_e64 v72, 1.0, v70, s[6:7]
	v_mul_f32_e32 v160, v161, v72
	v_mov_b32_e32 v72, v95
	v_pk_mul_f32 v[72:73], v[162:163], v[72:73]
	v_mul_f32_e32 v163, v71, v94
	v_mul_f32_e32 v162, v68, v163
	v_mul_f32_e32 v69, v69, v162
	v_mul_f32_e32 v68, v66, v69
	v_mul_f32_e32 v67, v67, v68
	v_mul_f32_e32 v66, v0, v67
	v_pk_mul_f32 v[152:153], v[152:153], v[68:69]
	v_mov_b32_e32 v0, v66
	v_mov_b32_e32 v68, v66
	s_nop 1
	v_permlane32_swap_b32_e32 v0, v68
	v_cndmask_b32_e64 v68, v0, v68, s[6:7]
	v_mul_f32_e32 v0, v95, v68
	v_cndmask_b32_e64 v0, v95, v0, s[6:7]
	v_mul_f32_e32 v0, v0, v70
	v_mov_b32_e32 v154, v94
	v_mov_b32_e32 v69, v66
	v_mov_b32_e32 v71, v95
	v_pk_mul_f32 v[156:157], v[156:157], v[162:163]
	v_pk_mul_f32 v[148:149], v[148:149], v[66:67]
	v_mul_f32_e32 v0, v161, v0
	v_pk_mul_f32 v[76:77], v[78:79], v[76:77]
	v_pk_mul_f32 v[78:79], v[150:151], v[154:155]
	v_pk_mul_f32 v[80:81], v[158:159], v[80:81]
	v_pk_mul_f32 v[66:67], v[68:69], v[70:71]
	v_pk_mul_f32 v[72:73], v[160:161], v[72:73] op_sel_hi:[0,1]
	v_pk_mul_f32 v[74:75], v[74:75], v[160:161] op_sel_hi:[1,0]
	v_pk_mul_f32 v[148:149], v[148:149], v[0:1] op_sel_hi:[1,0]
	v_pk_mul_f32 v[152:153], v[152:153], v[0:1] op_sel_hi:[1,0]
	v_pk_mul_f32 v[156:157], v[156:157], v[0:1] op_sel_hi:[1,0]
	v_pk_mul_f32 v[76:77], v[76:77], v[160:161] op_sel_hi:[1,0]
	v_pk_mul_f32 v[78:79], v[78:79], v[0:1] op_sel_hi:[1,0]
	v_pk_mul_f32 v[80:81], v[80:81], v[160:161] op_sel_hi:[1,0]
	v_mul_f32_e32 v0, v66, v67
	s_setprio 1
	v_cvt_pk_bf16_f32 v66, v148, v149
	v_cvt_pk_bf16_f32 v67, v152, v153
	v_cvt_pk_bf16_f32 v68, v156, v157
	v_cvt_pk_bf16_f32 v69, v78, v79
	v_mul_f32_e32 v234, v161, v0
	s_waitcnt lgkmcnt(0)
	v_mfma_f32_32x32x16_bf16 v[50:65], v[90:93], v[66:69], v[50:65]
	v_mfma_f32_32x32x16_bf16 v[34:49], v[136:139], v[66:69], v[34:49]
	v_mfma_f32_32x32x16_bf16 v[18:33], v[140:143], v[66:69], v[18:33]
	v_mfma_f32_32x32x16_bf16 v[2:17], v[144:147], v[66:69], v[2:17]
	v_cvt_pk_bf16_f32 v66, v72, v73
	v_cvt_pk_bf16_f32 v67, v74, v75
	v_cvt_pk_bf16_f32 v68, v76, v77
	v_cvt_pk_bf16_f32 v69, v80, v81
	s_nop 1
	v_mfma_f32_32x32x16_bf16 v[50:65], v[82:85], v[66:69], v[50:65]
	v_mfma_f32_32x32x16_bf16 v[34:49], v[86:89], v[66:69], v[34:49]
	v_mfma_f32_32x32x16_bf16 v[18:33], v[128:131], v[66:69], v[18:33]
	v_mfma_f32_32x32x16_bf16 v[2:17], v[132:135], v[66:69], v[2:17]
	s_setprio 0
